# short gated conv items handed out in reverse wave order so the workgroups that also run the context attention tasks get two conv items instead of three
# baseline (speedup 1.0000x reference)
; DI int otid() { int t = threadIdx.x; asm volatile("" : "+v"(t)); return t; }
; DI void phase_attn(const Params& P, int layer, char* smem) {
;     ...
;   const int tid = otid(), lane = tid & 63, w = tid >> 6;
;   const int gw = blockIdx.x * 8 + w, nw = gridDim.x * 8;
;   const h16* pa = (const h16*)(P.ws + WS_R1);
;   h16* ya = (h16*)(P.ws + WS_R2);
;   const int nitems = (last ? T_LAT : T_ALL) / 8;
;   const float* cw = P.conv_a + (size_t)layer * 3 * 512 + lane * 8;
;   float w0[8], w1[8], w2[8];
; #pragma unroll
;   for (int e = 0; e < 8; ++e) { w0[e] = cw[e]; w1[e] = cw[512 + e]; w2[e] = cw[1024 + e]; }
;   for (int it = gw; it < nitems; it += nw) {
;     const int tk0 = it * 8;
;     int t0, L;
;     if (tk0 < T_LAT) { t0 = tk0 & 2047; L = SEQ; } else { t0 = (tk0 - T_LAT) & 255; L = CTXL; }
.LBB0_91:
	v_mov_b32_e32 v1, v208
	s_and_b64 s[0:1], s[0:1], exec
	v_readlane_b32 s2, v254, 40
	v_ashrrev_i32_e32 v0, 6, v1
	s_movk_i32 s0, 0x1000
	s_cselect_b32 s41, s0, 0x1200
	s_load_dword s24, s[36:37], 0x0
	s_waitcnt lgkmcnt(0)
	s_lshl_b32 s24, s24, 3
	s_add_i32 s24, s24, -1
	s_sub_i32 s2, s24, s2
	v_sub_u32_e32 v54, s2, v0
	v_cmp_gt_i32_e32 vcc, s41, v54
	s_and_saveexec_b64 s[0:1], vcc
	s_cbranch_execz .LBB0_106
	s_load_dword s2, s[36:37], 0x10
	s_load_dword s24, s[36:37], 0x0
	s_mul_hi_i32 s25, s40, 0x1800
	s_mulk_i32 s40, 0x1800
	v_lshlrev_b32_e32 v1, 3, v1
	s_waitcnt lgkmcnt(0)
	s_lshr_b32 s2, s2, 16
	s_cmp_lg_u32 s2, 0
	s_cselect_b64 s[2:3], -1, 0
	s_cmp_lg_u64 s[2:3], 0
	s_addc_u32 s24, s24, 0
	v_readlane_b32 s52, v254, 50
	v_readlane_b32 s53, v254, 51
	s_add_u32 s2, s52, s40
	v_and_b32_e32 v1, 0x1f8, v1
	s_addc_u32 s3, s53, s25
	v_lshlrev_b32_e32 v128, 2, v1
	v_lshl_add_u64 v[2:3], s[2:3], 0, v[128:129]
	s_mov_b64 s[38:39], 0x1000
	global_load_dwordx4 v[24:27], v128, s[2:3] offset:16
	global_load_dwordx4 v[28:31], v128, s[2:3]
	global_load_dwordx4 v[32:35], v128, s[2:3] offset:2064
	global_load_dwordx4 v[36:39], v128, s[2:3] offset:2048
	s_movk_i32 s2, 0x1000
	v_lshl_add_u64 v[4:5], v[2:3], 0, s[38:39]
	v_add_co_u32_e32 v2, vcc, s2, v2
	v_readlane_b32 s2, v253, 35
	s_nop 0
	v_addc_co_u32_e32 v3, vcc, 0, v3, vcc
	global_load_dwordx4 v[40:43], v[2:3], off
	global_load_dwordx4 v[44:47], v[4:5], off offset:16
	v_lshlrev_b32_e32 v128, 1, v1
	v_readlane_b32 s3, v253, 36
	s_lshl_b32 s40, s24, 3
	v_lshl_add_u64 v[48:49], s[48:49], 0, v[128:129]
	v_lshl_add_u64 v[50:51], s[2:3], 0, v[128:129]
	v_readlane_b32 s2, v254, 34
	s_lshl_b32 s42, s24, 6
	s_mov_b64 s[38:39], 0
	v_lshlrev_b32_e32 v55, 3, v54
	v_readlane_b32 s54, v254, 52
	v_readlane_b32 s55, v254, 53
	v_readlane_b32 s56, v254, 54
	v_readlane_b32 s57, v254, 55
	v_readlane_b32 s58, v254, 56
	v_readlane_b32 s59, v254, 57
	v_readlane_b32 s60, v254, 58
	v_readlane_b32 s61, v254, 59
	v_readlane_b32 s62, v254, 60
	v_readlane_b32 s63, v254, 61
	v_readlane_b32 s64, v254, 62
	v_readlane_b32 s65, v254, 63
	v_readlane_b32 s66, v255, 0
	v_readlane_b32 s67, v255, 1
	s_branch .LBB0_94
